# combined: loop-edge rotation of the gemm1/gemm2/out K loops, dynamic (atomic counter per XCD group) hand-out of gemm2 tiles after the first, post-phase back-edge wait relaxed to the prefetched loads o
# speedup vs baseline: 1.0012x; 1.0012x over previous
; DI float bf2f(bf16_t b) { return __uint_as_float(((unsigned)b) << 16); }
; DI void post_phase(const Params& p, int l) {
;     ...
;   for (; tok < TOK; tok += step) {
;     float yn[8], vn[8], bn[8];
;     const int tn = tok + step < TOK ? tok + step : tok;
;     {
;       const bf16_t* vb = (const bf16_t*)(p.R + (size_t)tn * RS + 512) + 1024;
; #pragma unroll
;       for (int h = 0; h < 8; h++) {
;         yn[h] = __builtin_nontemporal_load(&p.yscan[(size_t)tn * 512 + h * 64 + lane]);
;         vn[h] = bf2f(vb[h * 64 + lane]);
;         bn[h] = p.bonus[(size_t)tn * 8 + h];
;       }
;     }
;     float o[8];
; #pragma unroll
;     for (int h = 0; h < 8; h++) {
;       const float mean = wave_sum(y[h]) * (1.f / 64.f);
;       const float dv = y[h] - mean;
;       const float var = wave_sum(dv * dv) * (1.f / 64.f);
;       o[h] = dv * rsqrtf(var + 64e-5f) * lw[h] + lb[h] + bo[h] * vv[h];
.Lpost_cont:
	global_load_dword v61, v[26:27], off nt
	global_load_ushort v25, v[6:7], off
	global_load_dword v63, v[26:27], off offset:256 nt
	global_load_ushort v46, v[74:75], off offset:128
	global_load_dwordx4 v[8:11], v[4:5], off offset:16
	s_nop 0
	global_load_dwordx4 v[4:7], v[4:5], off
	s_nop 0
	global_load_dword v64, v[26:27], off offset:512 nt
	global_load_ushort v47, v[74:75], off offset:256
	global_load_dword v65, v[26:27], off offset:768 nt
	global_load_ushort v48, v[74:75], off offset:384
	global_load_dword v66, v[26:27], off offset:1024 nt
	global_load_ushort v49, v[74:75], off offset:512
	global_load_dword v67, v[26:27], off offset:1280 nt
	global_load_ushort v50, v[74:75], off offset:640
	global_load_dword v68, v[26:27], off offset:1536 nt
	global_load_ushort v51, v[74:75], off offset:768
	global_load_dword v69, v[26:27], off offset:1792 nt
	global_load_ushort v52, v[74:75], off offset:896
	v_add_f32_dpp v26, v58, v58 quad_perm:[1,0,3,2] row_mask:0xf bank_mask:0xf bound_ctrl:1
	v_add_f32_dpp v74, v57, v57 quad_perm:[1,0,3,2] row_mask:0xf bank_mask:0xf bound_ctrl:1
	v_cmp_lt_i32_e32 vcc, s19, v59
	v_add_f32_dpp v26, v26, v26 quad_perm:[2,3,0,1] row_mask:0xf bank_mask:0xf bound_ctrl:1
	v_add_f32_dpp v74, v74, v74 quad_perm:[2,3,0,1] row_mask:0xf bank_mask:0xf bound_ctrl:1
	s_or_b64 s[10:11], vcc, s[10:11]
	v_add_f32_dpp v26, v26, v26 row_half_mirror row_mask:0xf bank_mask:0xf bound_ctrl:1
	v_add_f32_dpp v74, v74, v74 row_half_mirror row_mask:0xf bank_mask:0xf bound_ctrl:1
	s_nop 0
	v_add_f32_dpp v26, v26, v26 row_mirror row_mask:0xf bank_mask:0xf bound_ctrl:1
	v_add_f32_dpp v74, v74, v74 row_mirror row_mask:0xf bank_mask:0xf bound_ctrl:1
	v_readlane_b32 s6, v26, 16
	v_readlane_b32 s7, v26, 48
	v_readlane_b32 s4, v26, 0
	v_readlane_b32 s5, v26, 32
	v_mov_b32_e32 v26, s6
	v_mov_b32_e32 v27, s7
	v_pk_add_f32 v[26:27], s[4:5], v[26:27]
	s_nop 0
	v_add_f32_e32 v26, v26, v27
	v_fmac_f32_e32 v58, 0xbc800000, v26
	v_mul_f32_e32 v26, v58, v58
	v_mov_b32_e32 v27, v164
	s_nop 1
	v_mov_b32_dpp v27, v26 quad_perm:[1,0,3,2] row_mask:0xf bank_mask:0xf
	v_fmac_f32_e32 v27, v58, v58
	s_nop 1
	v_add_f32_dpp v26, v27, v27 quad_perm:[2,3,0,1] row_mask:0xf bank_mask:0xf bound_ctrl:1
	s_nop 1
	v_add_f32_dpp v26, v26, v26 row_half_mirror row_mask:0xf bank_mask:0xf bound_ctrl:1
	s_nop 1
	v_add_f32_dpp v26, v26, v26 row_mirror row_mask:0xf bank_mask:0xf bound_ctrl:1
	s_nop 0
	v_readlane_b32 s6, v26, 16
	v_readlane_b32 s7, v26, 48
	v_readlane_b32 s4, v26, 0
	v_readlane_b32 s5, v26, 32
	v_mov_b32_e32 v26, s6
	v_mov_b32_e32 v27, s7
	v_readlane_b32 s6, v74, 16
	v_readlane_b32 s7, v74, 48
	v_pk_add_f32 v[26:27], s[4:5], v[26:27]
	v_readlane_b32 s4, v74, 0
	v_readlane_b32 s5, v74, 32
	v_mov_b32_e32 v74, s6
	v_mov_b32_e32 v75, s7
	v_pk_add_f32 v[74:75], s[4:5], v[74:75]
	v_mov_b32_e32 v77, v26
	v_add_f32_e32 v74, v74, v75
	v_fmac_f32_e32 v57, 0xbc800000, v74
	v_mul_f32_e32 v74, v57, v57
	v_mov_b32_e32 v75, v164
	s_nop 1
	v_mov_b32_dpp v75, v74 quad_perm:[1,0,3,2] row_mask:0xf bank_mask:0xf
	v_fmac_f32_e32 v75, v57, v57
	s_nop 1
	v_add_f32_dpp v74, v75, v75 quad_perm:[2,3,0,1] row_mask:0xf bank_mask:0xf bound_ctrl:1
	s_nop 1
	v_add_f32_dpp v74, v74, v74 row_half_mirror row_mask:0xf bank_mask:0xf bound_ctrl:1
	s_nop 1
	v_add_f32_dpp v74, v74, v74 row_mirror row_mask:0xf bank_mask:0xf bound_ctrl:1
	s_nop 0
	v_readlane_b32 s6, v74, 16
	v_readlane_b32 s7, v74, 48
	v_readlane_b32 s4, v74, 0
	v_readlane_b32 s5, v74, 32
	v_mov_b32_e32 v74, s6
	v_mov_b32_e32 v75, s7
	v_pk_add_f32 v[74:75], s[4:5], v[74:75]
	s_mov_b32 s4, 0x3a27c5ac
	v_mov_b32_e32 v76, v74
	v_mov_b32_e32 v26, v75
	v_pk_add_f32 v[74:75], v[76:77], v[26:27]
	v_mov_b64_e32 v[26:27], s[4:5]
	v_pk_fma_f32 v[74:75], v[74:75], s[26:27], v[26:27] op_sel_hi:[1,0,0]
	s_nop 0
	v_mul_f32_e32 v76, 0x4b800000, v75
	v_cmp_gt_f32_e64 s[6:7], s3, v75
	v_cmp_gt_f32_e64 s[4:5], s3, v74
	s_nop 0
	v_cndmask_b32_e64 v75, v75, v76, s[6:7]
	v_rsq_f32_e32 v75, v75
	s_nop 0
	v_mul_f32_e32 v76, 0x45800000, v75
	v_cndmask_b32_e64 v75, v75, v76, s[6:7]
	v_mul_f32_e32 v58, v58, v75
	v_fma_f32 v58, v28, v58, v36
	v_fmac_f32_e32 v58, v16, v78
	v_mul_f32_e32 v16, 0x4b800000, v74
	v_cndmask_b32_e64 v16, v74, v16, s[4:5]
	v_rsq_f32_e32 v16, v16
	s_nop 0
	v_mul_f32_e32 v74, 0x45800000, v16
	v_cndmask_b32_e64 v16, v16, v74, s[4:5]
	v_mul_f32_e32 v16, v57, v16
	v_fma_f32 v16, v29, v16, v37
	v_fmac_f32_e32 v16, v17, v79
	v_add_f32_dpp v17, v56, v56 quad_perm:[1,0,3,2] row_mask:0xf bank_mask:0xf bound_ctrl:1
	v_mov_b32_e32 v57, v164
	s_nop 0
	v_add_f32_dpp v17, v17, v17 quad_perm:[2,3,0,1] row_mask:0xf bank_mask:0xf bound_ctrl:1
	s_nop 1
	v_add_f32_dpp v17, v17, v17 row_half_mirror row_mask:0xf bank_mask:0xf bound_ctrl:1
	s_nop 1
	v_add_f32_dpp v17, v17, v17 row_mirror row_mask:0xf bank_mask:0xf bound_ctrl:1
	s_nop 0
	v_readlane_b32 s6, v17, 16
	v_readlane_b32 s7, v17, 48
	v_readlane_b32 s4, v17, 0
	v_readlane_b32 s5, v17, 32
	v_mov_b32_e32 v74, s6
	v_mov_b32_e32 v75, s7
	v_pk_add_f32 v[74:75], s[4:5], v[74:75]
	s_nop 0
	v_add_f32_e32 v17, v74, v75
	v_fmac_f32_e32 v56, 0xbc800000, v17
	v_mul_f32_e32 v17, v56, v56
	s_nop 1
	v_mov_b32_dpp v57, v17 quad_perm:[1,0,3,2] row_mask:0xf bank_mask:0xf
	v_fmac_f32_e32 v57, v56, v56
	s_nop 1
	v_add_f32_dpp v17, v57, v57 quad_perm:[2,3,0,1] row_mask:0xf bank_mask:0xf bound_ctrl:1
	v_mov_b32_e32 v57, v164
	s_nop 0
	v_add_f32_dpp v17, v17, v17 row_half_mirror row_mask:0xf bank_mask:0xf bound_ctrl:1
	s_nop 1
	v_add_f32_dpp v17, v17, v17 row_mirror row_mask:0xf bank_mask:0xf bound_ctrl:1
	s_nop 0
	v_readlane_b32 s4, v17, 0
	v_readlane_b32 s6, v17, 16
	v_readlane_b32 s5, v17, 32
	v_readlane_b32 s7, v17, 48
; DI void post_phase(const Params& p, int l) {
;     ...
;     for (int h = 0; h < 8; h++) {
;       const float mean = wave_sum(y[h]) * (1.f / 64.f);
;       const float dv = y[h] - mean;
;       const float var = wave_sum(dv * dv) * (1.f / 64.f);
;       o[h] = dv * rsqrtf(var + 64e-5f) * lw[h] + lb[h] + bo[h] * vv[h];
	v_add_f32_dpp v17, v55, v55 quad_perm:[1,0,3,2] row_mask:0xf bank_mask:0xf bound_ctrl:1
	v_mov_b32_e32 v74, s6
	v_mov_b32_e32 v75, s7
	v_add_f32_dpp v17, v17, v17 quad_perm:[2,3,0,1] row_mask:0xf bank_mask:0xf bound_ctrl:1
	v_pk_add_f32 v[74:75], s[4:5], v[74:75]
	s_nop 0
	v_add_f32_dpp v17, v17, v17 row_half_mirror row_mask:0xf bank_mask:0xf bound_ctrl:1
	v_mov_b32_e32 v79, v74
	s_nop 0
	v_add_f32_dpp v17, v17, v17 row_mirror row_mask:0xf bank_mask:0xf bound_ctrl:1
	s_nop 0
	v_readlane_b32 s6, v17, 16
	v_readlane_b32 s7, v17, 48
	v_readlane_b32 s4, v17, 0
	v_readlane_b32 s5, v17, 32
	v_mov_b32_e32 v76, s6
	v_mov_b32_e32 v77, s7
	v_pk_add_f32 v[76:77], s[4:5], v[76:77]
	s_nop 0
	v_add_f32_e32 v17, v76, v77
	v_fmac_f32_e32 v55, 0xbc800000, v17
	v_mul_f32_e32 v17, v55, v55
	s_nop 1
	v_mov_b32_dpp v57, v17 quad_perm:[1,0,3,2] row_mask:0xf bank_mask:0xf
	v_fmac_f32_e32 v57, v55, v55
	s_nop 1
	v_add_f32_dpp v17, v57, v57 quad_perm:[2,3,0,1] row_mask:0xf bank_mask:0xf bound_ctrl:1
	s_nop 1
	v_add_f32_dpp v17, v17, v17 row_half_mirror row_mask:0xf bank_mask:0xf bound_ctrl:1
	s_nop 1
	v_add_f32_dpp v17, v17, v17 row_mirror row_mask:0xf bank_mask:0xf bound_ctrl:1
	s_nop 0
	v_readlane_b32 s6, v17, 16
	v_readlane_b32 s7, v17, 48
	v_readlane_b32 s4, v17, 0
	v_readlane_b32 s5, v17, 32
	v_mov_b32_e32 v76, s6
	v_mov_b32_e32 v77, s7
	v_pk_add_f32 v[76:77], s[4:5], v[76:77]
	s_nop 0
	v_mov_b32_e32 v78, v76
	v_mov_b32_e32 v74, v77
	v_pk_add_f32 v[74:75], v[78:79], v[74:75]
	s_nop 0
	v_pk_fma_f32 v[74:75], v[74:75], s[26:27], v[26:27] op_sel_hi:[1,0,0]
	s_nop 0
	v_mul_f32_e32 v17, 0x4b800000, v75
	v_cmp_gt_f32_e64 s[6:7], s3, v75
	v_cmp_gt_f32_e64 s[4:5], s3, v74
	s_nop 0
	v_cndmask_b32_e64 v17, v75, v17, s[6:7]
	v_rsq_f32_e32 v17, v17
	s_nop 0
	v_mul_f32_e32 v57, 0x45800000, v17
	v_cndmask_b32_e64 v17, v17, v57, s[6:7]
	v_mul_f32_e32 v17, v56, v17
	v_fma_f32 v17, v30, v17, v38
	v_fmac_f32_e32 v17, v18, v73
	v_mul_f32_e32 v18, 0x4b800000, v74
	v_cndmask_b32_e64 v18, v74, v18, s[4:5]
	v_rsq_f32_e32 v18, v18
	s_nop 0
	v_mul_f32_e32 v56, 0x45800000, v18
	v_cndmask_b32_e64 v18, v18, v56, s[4:5]
	v_mul_f32_e32 v18, v55, v18
	v_fma_f32 v18, v31, v18, v39
	v_fmac_f32_e32 v18, v19, v72
	v_add_f32_dpp v19, v54, v54 quad_perm:[1,0,3,2] row_mask:0xf bank_mask:0xf bound_ctrl:1
	v_mov_b32_e32 v55, v164
	s_nop 0
	v_add_f32_dpp v19, v19, v19 quad_perm:[2,3,0,1] row_mask:0xf bank_mask:0xf bound_ctrl:1
	s_nop 1
	v_add_f32_dpp v19, v19, v19 row_half_mirror row_mask:0xf bank_mask:0xf bound_ctrl:1
	s_nop 1
	v_add_f32_dpp v19, v19, v19 row_mirror row_mask:0xf bank_mask:0xf bound_ctrl:1
	s_nop 0
	v_readlane_b32 s6, v19, 16
	v_readlane_b32 s7, v19, 48
	v_readlane_b32 s4, v19, 0
	v_readlane_b32 s5, v19, 32
	v_mov_b32_e32 v56, s6
	v_mov_b32_e32 v57, s7
	v_pk_add_f32 v[56:57], s[4:5], v[56:57]
	s_nop 0
	v_add_f32_e32 v19, v56, v57
	v_fmac_f32_e32 v54, 0xbc800000, v19
	v_mul_f32_e32 v19, v54, v54
	s_nop 1
	v_mov_b32_dpp v55, v19 quad_perm:[1,0,3,2] row_mask:0xf bank_mask:0xf
	v_fmac_f32_e32 v55, v54, v54
	s_nop 1
	v_add_f32_dpp v19, v55, v55 quad_perm:[2,3,0,1] row_mask:0xf bank_mask:0xf bound_ctrl:1
	v_mov_b32_e32 v55, v164
	s_nop 0
	v_add_f32_dpp v19, v19, v19 row_half_mirror row_mask:0xf bank_mask:0xf bound_ctrl:1
	s_nop 1
	v_add_f32_dpp v19, v19, v19 row_mirror row_mask:0xf bank_mask:0xf bound_ctrl:1
	s_nop 0
	v_readlane_b32 s4, v19, 0
	v_readlane_b32 s6, v19, 16
	v_readlane_b32 s5, v19, 32
	v_readlane_b32 s7, v19, 48
	v_add_f32_dpp v19, v53, v53 quad_perm:[1,0,3,2] row_mask:0xf bank_mask:0xf bound_ctrl:1
	v_mov_b32_e32 v56, s6
	v_mov_b32_e32 v57, s7
	v_add_f32_dpp v19, v19, v19 quad_perm:[2,3,0,1] row_mask:0xf bank_mask:0xf bound_ctrl:1
	v_pk_add_f32 v[56:57], s[4:5], v[56:57]
	s_nop 0
	v_add_f32_dpp v19, v19, v19 row_half_mirror row_mask:0xf bank_mask:0xf bound_ctrl:1
	v_mov_b32_e32 v75, v56
	s_nop 0
	v_add_f32_dpp v19, v19, v19 row_mirror row_mask:0xf bank_mask:0xf bound_ctrl:1
	s_nop 0
	v_readlane_b32 s6, v19, 16
	v_readlane_b32 s7, v19, 48
	v_readlane_b32 s4, v19, 0
	v_readlane_b32 s5, v19, 32
	v_mov_b32_e32 v72, s6
	v_mov_b32_e32 v73, s7
	v_pk_add_f32 v[72:73], s[4:5], v[72:73]
	s_nop 0
	v_add_f32_e32 v19, v72, v73
	v_fmac_f32_e32 v53, 0xbc800000, v19
	v_mul_f32_e32 v19, v53, v53
	s_nop 1
	v_mov_b32_dpp v55, v19 quad_perm:[1,0,3,2] row_mask:0xf bank_mask:0xf
	v_fmac_f32_e32 v55, v53, v53
	s_nop 1
	v_add_f32_dpp v19, v55, v55 quad_perm:[2,3,0,1] row_mask:0xf bank_mask:0xf bound_ctrl:1
	s_nop 1
	v_add_f32_dpp v19, v19, v19 row_half_mirror row_mask:0xf bank_mask:0xf bound_ctrl:1
	s_nop 1
	v_add_f32_dpp v19, v19, v19 row_mirror row_mask:0xf bank_mask:0xf bound_ctrl:1
	s_nop 0
	v_readlane_b32 s6, v19, 16
	v_readlane_b32 s7, v19, 48
	v_readlane_b32 s4, v19, 0
	v_readlane_b32 s5, v19, 32
	v_mov_b32_e32 v72, s6
	v_mov_b32_e32 v73, s7
	v_pk_add_f32 v[72:73], s[4:5], v[72:73]
	s_nop 0
	v_mov_b32_e32 v74, v72
	v_mov_b32_e32 v56, v73
	v_pk_add_f32 v[56:57], v[74:75], v[56:57]
	s_nop 0
	v_pk_fma_f32 v[56:57], v[56:57], s[26:27], v[26:27] op_sel_hi:[1,0,0]
	s_nop 0
	v_mul_f32_e32 v19, 0x4b800000, v57
	v_cmp_gt_f32_e64 s[6:7], s3, v57
	v_cmp_gt_f32_e64 s[4:5], s3, v56
	s_nop 0
	v_cndmask_b32_e64 v19, v57, v19, s[6:7]
	v_rsq_f32_e32 v19, v19
	s_nop 0
	v_mul_f32_e32 v55, 0x45800000, v19
	v_cndmask_b32_e64 v19, v19, v55, s[6:7]
	v_mul_f32_e32 v19, v54, v19
	v_fma_f32 v19, v32, v19, v40
	v_fmac_f32_e32 v19, v12, v71
	v_mul_f32_e32 v12, 0x4b800000, v56
	v_cndmask_b32_e64 v12, v56, v12, s[4:5]
	v_rsq_f32_e32 v12, v12
	s_nop 0
	v_mul_f32_e32 v54, 0x45800000, v12
; DI bf16_t f2bf(float f) { return (bf16_t)(pack2(f, f) & 0xFFFFu); }
; DI float bf2f(bf16_t b) { return __uint_as_float(((unsigned)b) << 16); }
; DI void post_phase(const Params& p, int l) {
;     ...
;   for (; tok < TOK; tok += step) {
;     float yn[8], vn[8], bn[8];
;     const int tn = tok + step < TOK ? tok + step : tok;
;     {
;       const bf16_t* vb = (const bf16_t*)(p.R + (size_t)tn * RS + 512) + 1024;
; #pragma unroll
;       for (int h = 0; h < 8; h++) {
;         yn[h] = __builtin_nontemporal_load(&p.yscan[(size_t)tn * 512 + h * 64 + lane]);
;         vn[h] = bf2f(vb[h * 64 + lane]);
;         bn[h] = p.bonus[(size_t)tn * 8 + h];
;     ...
;     for (int h = 0; h < 8; h++) {
;       const float mean = wave_sum(y[h]) * (1.f / 64.f);
;       const float dv = y[h] - mean;
;       const float var = wave_sum(dv * dv) * (1.f / 64.f);
;       o[h] = dv * rsqrtf(var + 64e-5f) * lw[h] + lb[h] + bo[h] * vv[h];
;     }
; #pragma unroll
;     for (int h = 0; h < 8; h++) p.o_r[(size_t)tok * 512 + h * 64 + lane] = f2bf(o[h]);
; #pragma unroll
;     for (int h = 0; h < 8; h++) { y[h] = yn[h]; vv[h] = vn[h]; bo[h] = bn[h]; }
	v_cndmask_b32_e64 v12, v12, v54, s[4:5]
	v_mul_f32_e32 v12, v53, v12
	v_fma_f32 v53, v33, v12, v41
	v_fmac_f32_e32 v53, v13, v70
	v_add_f32_dpp v12, v45, v45 quad_perm:[1,0,3,2] row_mask:0xf bank_mask:0xf bound_ctrl:1
	v_add_f32_dpp v54, v44, v44 quad_perm:[1,0,3,2] row_mask:0xf bank_mask:0xf bound_ctrl:1
	s_nop 0
	v_add_f32_dpp v12, v12, v12 quad_perm:[2,3,0,1] row_mask:0xf bank_mask:0xf bound_ctrl:1
	v_add_f32_dpp v54, v54, v54 quad_perm:[2,3,0,1] row_mask:0xf bank_mask:0xf bound_ctrl:1
	s_nop 0
	v_add_f32_dpp v12, v12, v12 row_half_mirror row_mask:0xf bank_mask:0xf bound_ctrl:1
	v_add_f32_dpp v54, v54, v54 row_half_mirror row_mask:0xf bank_mask:0xf bound_ctrl:1
	s_nop 0
	v_add_f32_dpp v12, v12, v12 row_mirror row_mask:0xf bank_mask:0xf bound_ctrl:1
	v_add_f32_dpp v54, v54, v54 row_mirror row_mask:0xf bank_mask:0xf bound_ctrl:1
	v_readlane_b32 s6, v12, 16
	v_readlane_b32 s7, v12, 48
	v_readlane_b32 s4, v12, 0
	v_readlane_b32 s5, v12, 32
	v_mov_b32_e32 v12, s6
	v_mov_b32_e32 v13, s7
	v_pk_add_f32 v[12:13], s[4:5], v[12:13]
	s_nop 0
	v_add_f32_e32 v12, v12, v13
	v_fmac_f32_e32 v45, 0xbc800000, v12
	v_mul_f32_e32 v12, v45, v45
	v_mov_b32_e32 v13, v164
	s_nop 1
	v_mov_b32_dpp v13, v12 quad_perm:[1,0,3,2] row_mask:0xf bank_mask:0xf
	v_fmac_f32_e32 v13, v45, v45
	s_nop 1
	v_add_f32_dpp v12, v13, v13 quad_perm:[2,3,0,1] row_mask:0xf bank_mask:0xf bound_ctrl:1
	s_nop 1
	v_add_f32_dpp v12, v12, v12 row_half_mirror row_mask:0xf bank_mask:0xf bound_ctrl:1
	s_nop 1
	v_add_f32_dpp v12, v12, v12 row_mirror row_mask:0xf bank_mask:0xf bound_ctrl:1
	s_nop 0
	v_readlane_b32 s6, v12, 16
	v_readlane_b32 s7, v12, 48
	v_readlane_b32 s4, v12, 0
	v_readlane_b32 s5, v12, 32
	v_mov_b32_e32 v12, s6
	v_mov_b32_e32 v13, s7
	v_readlane_b32 s6, v54, 16
	v_readlane_b32 s7, v54, 48
	v_pk_add_f32 v[12:13], s[4:5], v[12:13]
	v_readlane_b32 s4, v54, 0
	v_readlane_b32 s5, v54, 32
	v_mov_b32_e32 v54, s6
	v_mov_b32_e32 v55, s7
	v_pk_add_f32 v[54:55], s[4:5], v[54:55]
	v_mov_b32_e32 v57, v12
	v_add_f32_e32 v54, v54, v55
	v_fmac_f32_e32 v44, 0xbc800000, v54
	v_mul_f32_e32 v54, v44, v44
	v_mov_b32_e32 v55, v164
	s_nop 1
	v_mov_b32_dpp v55, v54 quad_perm:[1,0,3,2] row_mask:0xf bank_mask:0xf
	v_fmac_f32_e32 v55, v44, v44
	s_nop 1
	v_add_f32_dpp v54, v55, v55 quad_perm:[2,3,0,1] row_mask:0xf bank_mask:0xf bound_ctrl:1
	s_nop 1
	v_add_f32_dpp v54, v54, v54 row_half_mirror row_mask:0xf bank_mask:0xf bound_ctrl:1
	s_nop 1
	v_add_f32_dpp v54, v54, v54 row_mirror row_mask:0xf bank_mask:0xf bound_ctrl:1
	s_nop 0
	v_readlane_b32 s6, v54, 16
	v_readlane_b32 s7, v54, 48
	v_readlane_b32 s4, v54, 0
	v_readlane_b32 s5, v54, 32
	v_mov_b32_e32 v54, s6
	v_mov_b32_e32 v55, s7
	v_pk_add_f32 v[54:55], s[4:5], v[54:55]
	s_nop 0
	v_mov_b32_e32 v56, v54
	v_mov_b32_e32 v12, v55
	v_pk_add_f32 v[12:13], v[56:57], v[12:13]
	s_waitcnt vmcnt(7)
	v_mov_b32_e32 v54, v66
	v_pk_fma_f32 v[12:13], v[12:13], s[26:27], v[26:27] op_sel_hi:[1,0,0]
	v_mov_b32_e32 v55, v65
	v_mul_f32_e32 v26, 0x4b800000, v13
	v_cmp_gt_f32_e64 s[6:7], s3, v13
	v_cmp_gt_f32_e64 s[4:5], s3, v12
	v_mov_b32_e32 v56, v64
	v_cndmask_b32_e64 v13, v13, v26, s[6:7]
	v_rsq_f32_e32 v13, v13
	v_mov_b32_e32 v57, v63
	v_mul_f32_e32 v26, 0x45800000, v13
	v_cndmask_b32_e64 v13, v13, v26, s[6:7]
	v_mul_f32_e32 v13, v45, v13
	v_fma_f32 v13, v34, v13, v42
	v_fmac_f32_e32 v13, v14, v62
	v_mul_f32_e32 v14, 0x4b800000, v12
	v_cndmask_b32_e64 v12, v12, v14, s[4:5]
	v_rsq_f32_e32 v12, v12
	v_cvt_pk_bf16_f32 v13, v13, s0
	global_store_short v[22:23], v13, off offset:768
	s_waitcnt vmcnt(4)
	v_mov_b32_e32 v45, v68
	v_mul_f32_e32 v14, 0x45800000, v12
	v_cndmask_b32_e64 v12, v12, v14, s[4:5]
	v_cvt_pk_bf16_f32 v14, v58, s0
	global_store_short v[22:23], v14, off
	v_cvt_pk_bf16_f32 v14, v16, s0
	v_mul_f32_e32 v12, v44, v12
	global_store_short v[22:23], v14, off offset:128
	v_cvt_pk_bf16_f32 v14, v17, s0
	v_fma_f32 v12, v35, v12, v43
	global_store_short v[22:23], v14, off offset:256
	v_cvt_pk_bf16_f32 v14, v18, s0
	v_fmac_f32_e32 v12, v15, v60
	global_store_short v[22:23], v14, off offset:384
	v_cvt_pk_bf16_f32 v14, v19, s0
	global_store_short v[22:23], v14, off offset:512
	v_cvt_pk_bf16_f32 v14, v53, s0
	v_cvt_pk_bf16_f32 v12, v12, s0
	global_store_short v[22:23], v14, off offset:640
	global_store_short v[22:23], v12, off offset:896
	v_lshl_add_u64 v[22:23], v[22:23], 0, s[22:23]
	s_waitcnt vmcnt(9)
	v_mov_b32_e32 v44, v69
	v_mov_b32_e32 v53, v67
	v_mov_b32_e32 v58, v61
	v_mov_b32_e32 v26, v59
	v_mov_b64_e32 v[14:15], v[10:11]
	v_mov_b64_e32 v[12:13], v[8:9]
	v_mov_b64_e32 v[18:19], v[6:7]
	v_mov_b64_e32 v[16:17], v[4:5]
	s_andn2_b64 exec, exec, s[10:11]
	s_cbranch_execnz .Lpost_top2
	s_branch .LBB0_1688
.Lpost_top2:
	v_add_u32_e32 v59, s18, v26
	v_cmp_gt_i32_e64 s[4:5], s20, v59
	v_mov_b64_e32 v[6:7], s[8:9]
	s_waitcnt vmcnt(8)
	v_lshlrev_b32_e32 v78, 16, v25
	v_cndmask_b32_e64 v4, v26, v59, s[4:5]
	v_mad_i64_i32 v[6:7], s[4:5], v4, s78, v[6:7]
	v_mov_b32_e32 v25, v164
	v_ashrrev_i32_e32 v5, 31, v4
	v_lshl_add_u64 v[6:7], v[6:7], 0, v[24:25]
	v_lshlrev_b64 v[8:9], 11, v[4:5]
	v_lshlrev_b64 v[4:5], 5, v[4:5]
	v_lshl_add_u64 v[74:75], v[6:7], 0, s[24:25]
	v_add_co_u32_e64 v6, s[4:5], s94, v6
	v_lshl_add_u64 v[26:27], v[20:21], 0, v[8:9]
	v_lshl_add_u64 v[4:5], s[14:15], 0, v[4:5]
	v_addc_co_u32_e64 v7, s[4:5], 0, v7, s[4:5]
	v_lshlrev_b32_e32 v79, 16, v46
	v_lshlrev_b32_e32 v73, 16, v47
	v_lshlrev_b32_e32 v72, 16, v48
	v_lshlrev_b32_e32 v71, 16, v49
	v_lshlrev_b32_e32 v70, 16, v50
	v_lshlrev_b32_e32 v62, 16, v51
	v_lshlrev_b32_e32 v60, 16, v52
	s_branch .Lpost_cont
